# P1/P12 idle-tail fp8 weight conversion loops: the item's 32 row loads issued back to back before the conversion arithmetic (no vmcnt waits inside the burst)
# baseline (speedup 1.0000x reference)
.LBB0_232:
	s_and_b32 s4, s7, 0xffffff80
	v_add_u32_e32 v0, s4, v132
	v_ashrrev_i32_e32 v1, 31, v0
	s_and_b32 s2, s11, 0xfc0
	v_lshlrev_b64 v[0:1], 14, v[0:1]
	v_lshl_add_u64 v[0:1], s[66:67], 0, v[0:1]
	s_lshl_b32 s0, s2, 2
	v_lshl_add_u64 v[0:1], v[0:1], 0, s[0:1]
	v_lshl_add_u64 v[4:5], v[0:1], 0, v[128:129]
	v_add_co_u32_e32 v0, vcc, 0x4000, v4
	global_load_dwordx4 v[120:123], v[4:5], off nt
	s_nop 0
	v_addc_co_u32_e32 v1, vcc, 0, v5, vcc
	global_load_dwordx4 v[124:127], v[0:1], off nt
	v_add_co_u32_e32 v0, vcc, 0x8000, v4
	s_nop 1
	s_nop 0
	v_addc_co_u32_e32 v1, vcc, 0, v5, vcc
	global_load_dwordx4 v[112:115], v[0:1], off nt
	v_add_co_u32_e32 v0, vcc, 0xc000, v4
	s_nop 1
	s_ashr_i32 s5, s4, 31
	s_nop 0
	v_addc_co_u32_e32 v1, vcc, 0, v5, vcc
	global_load_dwordx4 v[116:119], v[0:1], off nt
	v_add_co_u32_e32 v0, vcc, 0x40000, v4
	s_nop 1
	s_add_i32 s3, s3, s6
	s_nop 0
	v_addc_co_u32_e32 v1, vcc, 0, v5, vcc
	global_load_dwordx4 v[104:107], v[0:1], off nt
	v_add_co_u32_e32 v0, vcc, 0x44000, v4
	s_nop 1
	s_add_i32 s7, s7, s10
	s_nop 0
	v_addc_co_u32_e32 v1, vcc, 0, v5, vcc
	global_load_dwordx4 v[108:111], v[0:1], off nt
	v_add_co_u32_e32 v0, vcc, 0x48000, v4
	s_nop 1
	s_add_i32 s11, s11, s12
	s_nop 0
	v_addc_co_u32_e32 v1, vcc, 0, v5, vcc
	global_load_dwordx4 v[96:99], v[0:1], off nt
	v_add_co_u32_e32 v0, vcc, 0x4c000, v4
	s_nop 1
	s_cmpk_lt_i32 s3, 0x1580
	s_nop 0
	v_addc_co_u32_e32 v1, vcc, 0, v5, vcc
	global_load_dwordx4 v[100:103], v[0:1], off nt
	v_add_co_u32_e32 v0, vcc, 0x80000, v4
	s_nop 1
	v_addc_co_u32_e32 v1, vcc, 0, v5, vcc
	global_load_dwordx4 v[88:91], v[0:1], off nt
	v_add_co_u32_e32 v0, vcc, 0x84000, v4
	s_nop 1
	v_addc_co_u32_e32 v1, vcc, 0, v5, vcc
	global_load_dwordx4 v[92:95], v[0:1], off nt
	v_add_co_u32_e32 v0, vcc, 0x88000, v4
	s_nop 1
	s_nop 0
	v_addc_co_u32_e32 v1, vcc, 0, v5, vcc
	global_load_dwordx4 v[80:83], v[0:1], off nt
	v_add_co_u32_e32 v0, vcc, 0x8c000, v4
	s_nop 1
	s_nop 0
	v_addc_co_u32_e32 v1, vcc, 0, v5, vcc
	global_load_dwordx4 v[84:87], v[0:1], off nt
	v_add_co_u32_e32 v0, vcc, 0xc0000, v4
	s_nop 1
	s_nop 0
	v_addc_co_u32_e32 v1, vcc, 0, v5, vcc
	global_load_dwordx4 v[72:75], v[0:1], off nt
	v_add_co_u32_e32 v0, vcc, 0xc4000, v4
	s_nop 1
	v_addc_co_u32_e32 v1, vcc, 0, v5, vcc
	global_load_dwordx4 v[76:79], v[0:1], off nt
	v_add_co_u32_e32 v0, vcc, 0xc8000, v4
	s_nop 1
	v_addc_co_u32_e32 v1, vcc, 0, v5, vcc
	global_load_dwordx4 v[64:67], v[0:1], off nt
	v_add_co_u32_e32 v0, vcc, 0xcc000, v4
	s_nop 1
	s_nop 0
	v_addc_co_u32_e32 v1, vcc, 0, v5, vcc
	global_load_dwordx4 v[68:71], v[0:1], off nt
	v_add_co_u32_e32 v0, vcc, 0x100000, v4
	s_nop 1
	s_nop 0
	v_addc_co_u32_e32 v1, vcc, 0, v5, vcc
	global_load_dwordx4 v[56:59], v[0:1], off nt
	v_add_co_u32_e32 v0, vcc, 0x104000, v4
	s_nop 1
	v_addc_co_u32_e32 v1, vcc, 0, v5, vcc
	global_load_dwordx4 v[60:63], v[0:1], off nt
	v_add_co_u32_e32 v0, vcc, 0x108000, v4
	s_nop 1
	v_addc_co_u32_e32 v1, vcc, 0, v5, vcc
	global_load_dwordx4 v[48:51], v[0:1], off nt
	v_add_co_u32_e32 v0, vcc, 0x10c000, v4
	s_nop 1
	s_nop 0
	v_addc_co_u32_e32 v1, vcc, 0, v5, vcc
	global_load_dwordx4 v[52:55], v[0:1], off nt
	v_add_co_u32_e32 v0, vcc, 0x140000, v4
	s_nop 1
	s_nop 0
	v_addc_co_u32_e32 v1, vcc, 0, v5, vcc
	global_load_dwordx4 v[40:43], v[0:1], off nt
	v_add_co_u32_e32 v0, vcc, 0x144000, v4
	s_nop 1
	v_addc_co_u32_e32 v1, vcc, 0, v5, vcc
	global_load_dwordx4 v[44:47], v[0:1], off nt
	v_add_co_u32_e32 v0, vcc, 0x148000, v4
	s_nop 1
	v_addc_co_u32_e32 v1, vcc, 0, v5, vcc
	global_load_dwordx4 v[32:35], v[0:1], off nt
	v_add_co_u32_e32 v0, vcc, 0x14c000, v4
	s_nop 1
	s_nop 0
	v_addc_co_u32_e32 v1, vcc, 0, v5, vcc
	global_load_dwordx4 v[36:39], v[0:1], off nt
	v_add_co_u32_e32 v0, vcc, 0x180000, v4
	s_nop 1
	s_nop 0
	v_addc_co_u32_e32 v1, vcc, 0, v5, vcc
	global_load_dwordx4 v[24:27], v[0:1], off nt
	v_add_co_u32_e32 v0, vcc, 0x184000, v4
	s_nop 1
	v_addc_co_u32_e32 v1, vcc, 0, v5, vcc
	global_load_dwordx4 v[28:31], v[0:1], off nt
	v_add_co_u32_e32 v0, vcc, 0x188000, v4
	s_nop 1
	v_addc_co_u32_e32 v1, vcc, 0, v5, vcc
	global_load_dwordx4 v[16:19], v[0:1], off nt
	v_add_co_u32_e32 v0, vcc, 0x18c000, v4
	s_nop 1
	s_nop 0
	v_addc_co_u32_e32 v1, vcc, 0, v5, vcc
	global_load_dwordx4 v[20:23], v[0:1], off nt
	v_add_co_u32_e32 v0, vcc, 0x1c0000, v4
	s_nop 1
	s_nop 0
	v_addc_co_u32_e32 v1, vcc, 0, v5, vcc
	global_load_dwordx4 v[8:11], v[0:1], off nt
	v_add_co_u32_e32 v0, vcc, 0x1c4000, v4
	s_nop 1
	v_addc_co_u32_e32 v1, vcc, 0, v5, vcc
	global_load_dwordx4 v[12:15], v[0:1], off nt
	v_add_co_u32_e32 v0, vcc, 0x1c8000, v4
	s_nop 1
	v_addc_co_u32_e32 v1, vcc, 0, v5, vcc
	v_add_co_u32_e32 v4, vcc, 0x1cc000, v4
	s_nop 1
	s_nop 0
	v_addc_co_u32_e32 v5, vcc, 0, v5, vcc
	global_load_dwordx4 v[0:3], v[0:1], off nt
	global_load_dwordx4 v[4:7], v[4:5], off nt
	v_mov_b32_e32 v158, 0
	s_waitcnt vmcnt(31)
	v_mul_f32_e32 v120, 0x43000000, v120
	s_waitcnt vmcnt(30)
	v_mul_f32_e32 v124, 0x43000000, v124
	v_med3_f32 v120, v120, s13, v149
	v_med3_f32 v124, v124, s13, v149
	v_cvt_pk_fp8_f32 v158, v120, v124
	s_waitcnt vmcnt(29)
	v_mul_f32_e32 v112, 0x43000000, v112
	s_waitcnt vmcnt(28)
	v_mul_f32_e32 v116, 0x43000000, v116
	v_med3_f32 v112, v112, s13, v149
	v_med3_f32 v116, v116, s13, v149
	v_cvt_pk_fp8_f32 v158, v112, v116 op_sel:[0,0,1]
	v_mul_f32_e32 v112, 0x43000000, v121
	v_mul_f32_e32 v116, 0x43000000, v125
	v_med3_f32 v112, v112, s13, v149
	v_med3_f32 v116, v116, s13, v149
	v_mov_b32_e32 v120, 0
	v_cvt_pk_fp8_f32 v120, v112, v116
	v_mul_f32_e32 v112, 0x43000000, v113
	v_mul_f32_e32 v113, 0x43000000, v117
	v_med3_f32 v112, v112, s13, v149
	v_med3_f32 v113, v113, s13, v149
	v_cvt_pk_fp8_f32 v120, v112, v113 op_sel:[0,0,1]
	v_mul_f32_e32 v112, 0x43000000, v122
	v_mul_f32_e32 v113, 0x43000000, v126
	v_med3_f32 v112, v112, s13, v149
	v_med3_f32 v113, v113, s13, v149
	v_mov_b32_e32 v116, 0
	v_cvt_pk_fp8_f32 v116, v112, v113
	v_mul_f32_e32 v112, 0x43000000, v114
	v_mul_f32_e32 v113, 0x43000000, v118
	v_med3_f32 v112, v112, s13, v149
	v_med3_f32 v113, v113, s13, v149
	v_cvt_pk_fp8_f32 v116, v112, v113 op_sel:[0,0,1]
	v_mul_f32_e32 v112, 0x43000000, v123
	v_mul_f32_e32 v113, 0x43000000, v127
	v_med3_f32 v112, v112, s13, v149
	v_med3_f32 v113, v113, s13, v149
	v_mov_b32_e32 v114, 0
	v_cvt_pk_fp8_f32 v114, v112, v113
	v_mul_f32_e32 v112, 0x43000000, v115
	v_mul_f32_e32 v113, 0x43000000, v119
	v_med3_f32 v112, v112, s13, v149
	v_med3_f32 v113, v113, s13, v149
	s_waitcnt vmcnt(27)
	v_mul_f32_e32 v104, 0x43000000, v104
	s_waitcnt vmcnt(26)
	v_mul_f32_e32 v108, 0x43000000, v108
	v_cvt_pk_fp8_f32 v114, v112, v113 op_sel:[0,0,1]
	v_med3_f32 v104, v104, s13, v149
	v_med3_f32 v108, v108, s13, v149
	v_mov_b32_e32 v112, 0
	v_cvt_pk_fp8_f32 v112, v104, v108
	s_waitcnt vmcnt(25)
	v_mul_f32_e32 v96, 0x43000000, v96
	s_waitcnt vmcnt(24)
	v_mul_f32_e32 v100, 0x43000000, v100
	v_med3_f32 v96, v96, s13, v149
	v_med3_f32 v100, v100, s13, v149
	v_cvt_pk_fp8_f32 v112, v96, v100 op_sel:[0,0,1]
	v_mul_f32_e32 v96, 0x43000000, v105
	v_mul_f32_e32 v100, 0x43000000, v109
	v_med3_f32 v96, v96, s13, v149
	v_med3_f32 v100, v100, s13, v149
	v_mov_b32_e32 v104, 0
	v_cvt_pk_fp8_f32 v104, v96, v100
	v_mul_f32_e32 v96, 0x43000000, v97
	v_mul_f32_e32 v97, 0x43000000, v101
	v_med3_f32 v96, v96, s13, v149
	v_med3_f32 v97, v97, s13, v149
	v_cvt_pk_fp8_f32 v104, v96, v97 op_sel:[0,0,1]
	v_mul_f32_e32 v96, 0x43000000, v106
	v_mul_f32_e32 v97, 0x43000000, v110
	v_med3_f32 v96, v96, s13, v149
	v_med3_f32 v97, v97, s13, v149
	v_mov_b32_e32 v100, 0
	v_cvt_pk_fp8_f32 v100, v96, v97
	v_mul_f32_e32 v96, 0x43000000, v98
	v_mul_f32_e32 v97, 0x43000000, v102
	v_med3_f32 v96, v96, s13, v149
	v_med3_f32 v97, v97, s13, v149
	v_cvt_pk_fp8_f32 v100, v96, v97 op_sel:[0,0,1]
	v_mul_f32_e32 v96, 0x43000000, v107
	v_mul_f32_e32 v97, 0x43000000, v111
	v_med3_f32 v96, v96, s13, v149
	v_med3_f32 v97, v97, s13, v149
	v_mov_b32_e32 v98, 0
	v_cvt_pk_fp8_f32 v98, v96, v97
	v_mul_f32_e32 v96, 0x43000000, v99
	v_mul_f32_e32 v97, 0x43000000, v103
	v_med3_f32 v96, v96, s13, v149
	v_med3_f32 v97, v97, s13, v149
	s_waitcnt vmcnt(23)
	v_mul_f32_e32 v88, 0x43000000, v88
	s_waitcnt vmcnt(22)
	v_mul_f32_e32 v92, 0x43000000, v92
	v_cvt_pk_fp8_f32 v98, v96, v97 op_sel:[0,0,1]
	v_med3_f32 v88, v88, s13, v149
	v_med3_f32 v92, v92, s13, v149
	v_mov_b32_e32 v96, 0
	v_cvt_pk_fp8_f32 v96, v88, v92
	s_waitcnt vmcnt(21)
	v_mul_f32_e32 v80, 0x43000000, v80
	s_waitcnt vmcnt(20)
	v_mul_f32_e32 v84, 0x43000000, v84
	v_med3_f32 v80, v80, s13, v149
	v_med3_f32 v84, v84, s13, v149
	v_cvt_pk_fp8_f32 v96, v80, v84 op_sel:[0,0,1]
	v_mul_f32_e32 v80, 0x43000000, v89
	v_mul_f32_e32 v84, 0x43000000, v93
	v_med3_f32 v80, v80, s13, v149
	v_med3_f32 v84, v84, s13, v149
	v_mov_b32_e32 v88, 0
	v_cvt_pk_fp8_f32 v88, v80, v84
	v_mul_f32_e32 v80, 0x43000000, v81
	v_mul_f32_e32 v81, 0x43000000, v85
	v_med3_f32 v80, v80, s13, v149
	v_med3_f32 v81, v81, s13, v149
	v_cvt_pk_fp8_f32 v88, v80, v81 op_sel:[0,0,1]
	v_mul_f32_e32 v80, 0x43000000, v90
	v_mul_f32_e32 v81, 0x43000000, v94
	v_med3_f32 v80, v80, s13, v149
	v_med3_f32 v81, v81, s13, v149
	v_mov_b32_e32 v84, 0
	v_cvt_pk_fp8_f32 v84, v80, v81
	v_mul_f32_e32 v80, 0x43000000, v82
	v_mul_f32_e32 v81, 0x43000000, v86
	v_med3_f32 v80, v80, s13, v149
	v_med3_f32 v81, v81, s13, v149
	v_cvt_pk_fp8_f32 v84, v80, v81 op_sel:[0,0,1]
	v_mul_f32_e32 v80, 0x43000000, v91
	v_mul_f32_e32 v81, 0x43000000, v95
	v_med3_f32 v80, v80, s13, v149
	v_med3_f32 v81, v81, s13, v149
	v_mov_b32_e32 v82, 0
	v_cvt_pk_fp8_f32 v82, v80, v81
	v_mul_f32_e32 v80, 0x43000000, v83
	v_mul_f32_e32 v81, 0x43000000, v87
	v_med3_f32 v80, v80, s13, v149
	v_med3_f32 v81, v81, s13, v149
	s_waitcnt vmcnt(19)
	v_mul_f32_e32 v72, 0x43000000, v72
	s_waitcnt vmcnt(18)
	v_mul_f32_e32 v76, 0x43000000, v76
	v_cvt_pk_fp8_f32 v82, v80, v81 op_sel:[0,0,1]
	v_med3_f32 v72, v72, s13, v149
	v_med3_f32 v76, v76, s13, v149
	v_mov_b32_e32 v80, 0
	v_cvt_pk_fp8_f32 v80, v72, v76
	s_waitcnt vmcnt(17)
	v_mul_f32_e32 v64, 0x43000000, v64
	s_waitcnt vmcnt(16)
	v_mul_f32_e32 v68, 0x43000000, v68
	v_med3_f32 v64, v64, s13, v149
	v_med3_f32 v68, v68, s13, v149
	v_cvt_pk_fp8_f32 v80, v64, v68 op_sel:[0,0,1]
	v_mul_f32_e32 v64, 0x43000000, v73
	v_mul_f32_e32 v68, 0x43000000, v77
	v_med3_f32 v64, v64, s13, v149
	v_med3_f32 v68, v68, s13, v149
	v_mov_b32_e32 v72, 0
	v_cvt_pk_fp8_f32 v72, v64, v68
	v_mul_f32_e32 v64, 0x43000000, v65
	v_mul_f32_e32 v65, 0x43000000, v69
	v_med3_f32 v64, v64, s13, v149
	v_med3_f32 v65, v65, s13, v149
	v_cvt_pk_fp8_f32 v72, v64, v65 op_sel:[0,0,1]
	v_mul_f32_e32 v64, 0x43000000, v74
	v_mul_f32_e32 v65, 0x43000000, v78
	v_med3_f32 v64, v64, s13, v149
	v_med3_f32 v65, v65, s13, v149
	v_mov_b32_e32 v68, 0
	v_cvt_pk_fp8_f32 v68, v64, v65
	v_mul_f32_e32 v64, 0x43000000, v66
	v_mul_f32_e32 v65, 0x43000000, v70
	v_med3_f32 v64, v64, s13, v149
	v_med3_f32 v65, v65, s13, v149
	v_cvt_pk_fp8_f32 v68, v64, v65 op_sel:[0,0,1]
	v_mul_f32_e32 v64, 0x43000000, v75
	v_mul_f32_e32 v65, 0x43000000, v79
	v_med3_f32 v64, v64, s13, v149
	v_med3_f32 v65, v65, s13, v149
	v_mov_b32_e32 v66, 0
	v_cvt_pk_fp8_f32 v66, v64, v65
	v_mul_f32_e32 v64, 0x43000000, v67
	v_mul_f32_e32 v65, 0x43000000, v71
	v_med3_f32 v64, v64, s13, v149
	v_med3_f32 v65, v65, s13, v149
	s_waitcnt vmcnt(15)
	v_mul_f32_e32 v56, 0x43000000, v56
	s_waitcnt vmcnt(14)
	v_mul_f32_e32 v60, 0x43000000, v60
	v_cvt_pk_fp8_f32 v66, v64, v65 op_sel:[0,0,1]
	v_med3_f32 v56, v56, s13, v149
	v_med3_f32 v60, v60, s13, v149
	v_mov_b32_e32 v64, 0
	v_cvt_pk_fp8_f32 v64, v56, v60
	s_waitcnt vmcnt(13)
	v_mul_f32_e32 v48, 0x43000000, v48
	s_waitcnt vmcnt(12)
	v_mul_f32_e32 v52, 0x43000000, v52
	v_med3_f32 v48, v48, s13, v149
	v_med3_f32 v52, v52, s13, v149
	v_cvt_pk_fp8_f32 v64, v48, v52 op_sel:[0,0,1]
	v_mul_f32_e32 v48, 0x43000000, v57
	v_mul_f32_e32 v52, 0x43000000, v61
	v_med3_f32 v48, v48, s13, v149
	v_med3_f32 v52, v52, s13, v149
	v_mov_b32_e32 v56, 0
	v_cvt_pk_fp8_f32 v56, v48, v52
	v_mul_f32_e32 v48, 0x43000000, v49
	v_mul_f32_e32 v49, 0x43000000, v53
	v_med3_f32 v48, v48, s13, v149
	v_med3_f32 v49, v49, s13, v149
	v_cvt_pk_fp8_f32 v56, v48, v49 op_sel:[0,0,1]
	v_mul_f32_e32 v48, 0x43000000, v58
	v_mul_f32_e32 v49, 0x43000000, v62
	v_med3_f32 v48, v48, s13, v149
	v_med3_f32 v49, v49, s13, v149
	v_mov_b32_e32 v52, 0
	v_cvt_pk_fp8_f32 v52, v48, v49
	v_mul_f32_e32 v48, 0x43000000, v50
	v_mul_f32_e32 v49, 0x43000000, v54
	v_med3_f32 v48, v48, s13, v149
	v_med3_f32 v49, v49, s13, v149
	v_cvt_pk_fp8_f32 v52, v48, v49 op_sel:[0,0,1]
	v_mul_f32_e32 v48, 0x43000000, v59
	v_mul_f32_e32 v49, 0x43000000, v63
	v_med3_f32 v48, v48, s13, v149
	v_med3_f32 v49, v49, s13, v149
	v_mov_b32_e32 v50, 0
	v_cvt_pk_fp8_f32 v50, v48, v49
	v_mul_f32_e32 v48, 0x43000000, v51
	v_mul_f32_e32 v49, 0x43000000, v55
	v_med3_f32 v48, v48, s13, v149
	v_med3_f32 v49, v49, s13, v149
	s_waitcnt vmcnt(11)
	v_mul_f32_e32 v40, 0x43000000, v40
	s_waitcnt vmcnt(10)
	v_mul_f32_e32 v44, 0x43000000, v44
	v_cvt_pk_fp8_f32 v50, v48, v49 op_sel:[0,0,1]
	v_med3_f32 v40, v40, s13, v149
	v_med3_f32 v44, v44, s13, v149
	v_mov_b32_e32 v48, 0
	v_cvt_pk_fp8_f32 v48, v40, v44
	s_waitcnt vmcnt(9)
	v_mul_f32_e32 v32, 0x43000000, v32
	s_waitcnt vmcnt(8)
	v_mul_f32_e32 v36, 0x43000000, v36
	v_med3_f32 v32, v32, s13, v149
	v_med3_f32 v36, v36, s13, v149
	v_cvt_pk_fp8_f32 v48, v32, v36 op_sel:[0,0,1]
	v_mul_f32_e32 v32, 0x43000000, v41
	v_mul_f32_e32 v36, 0x43000000, v45
	v_med3_f32 v32, v32, s13, v149
	v_med3_f32 v36, v36, s13, v149
	v_mov_b32_e32 v40, 0
	v_cvt_pk_fp8_f32 v40, v32, v36
	v_mul_f32_e32 v32, 0x43000000, v33
	v_mul_f32_e32 v33, 0x43000000, v37
	v_med3_f32 v32, v32, s13, v149
	v_med3_f32 v33, v33, s13, v149
	v_cvt_pk_fp8_f32 v40, v32, v33 op_sel:[0,0,1]
	v_mul_f32_e32 v32, 0x43000000, v42
	v_mul_f32_e32 v33, 0x43000000, v46
	v_med3_f32 v32, v32, s13, v149
	v_med3_f32 v33, v33, s13, v149
	v_mov_b32_e32 v36, 0
	v_cvt_pk_fp8_f32 v36, v32, v33
	v_mul_f32_e32 v32, 0x43000000, v34
	v_mul_f32_e32 v33, 0x43000000, v38
	v_med3_f32 v32, v32, s13, v149
	v_med3_f32 v33, v33, s13, v149
	v_cvt_pk_fp8_f32 v36, v32, v33 op_sel:[0,0,1]
	v_mul_f32_e32 v32, 0x43000000, v43
	v_mul_f32_e32 v33, 0x43000000, v47
	v_med3_f32 v32, v32, s13, v149
	v_med3_f32 v33, v33, s13, v149
	v_mov_b32_e32 v34, 0
	v_cvt_pk_fp8_f32 v34, v32, v33
	v_mul_f32_e32 v32, 0x43000000, v35
	v_mul_f32_e32 v33, 0x43000000, v39
	v_med3_f32 v32, v32, s13, v149
	v_med3_f32 v33, v33, s13, v149
	s_waitcnt vmcnt(7)
	v_mul_f32_e32 v24, 0x43000000, v24
	s_waitcnt vmcnt(6)
	v_mul_f32_e32 v28, 0x43000000, v28
	v_cvt_pk_fp8_f32 v34, v32, v33 op_sel:[0,0,1]
	v_med3_f32 v24, v24, s13, v149
	v_med3_f32 v28, v28, s13, v149
	v_mov_b32_e32 v32, 0
	v_cvt_pk_fp8_f32 v32, v24, v28
	s_waitcnt vmcnt(5)
	v_mul_f32_e32 v16, 0x43000000, v16
	s_waitcnt vmcnt(4)
	v_mul_f32_e32 v20, 0x43000000, v20
	v_med3_f32 v16, v16, s13, v149
	v_med3_f32 v20, v20, s13, v149
	v_cvt_pk_fp8_f32 v32, v16, v20 op_sel:[0,0,1]
	v_mul_f32_e32 v16, 0x43000000, v25
	v_mul_f32_e32 v20, 0x43000000, v29
	v_med3_f32 v16, v16, s13, v149
	v_med3_f32 v20, v20, s13, v149
	v_mov_b32_e32 v24, 0
	v_cvt_pk_fp8_f32 v24, v16, v20
	v_mul_f32_e32 v16, 0x43000000, v17
	v_mul_f32_e32 v17, 0x43000000, v21
	v_med3_f32 v16, v16, s13, v149
	v_med3_f32 v17, v17, s13, v149
	v_cvt_pk_fp8_f32 v24, v16, v17 op_sel:[0,0,1]
	v_mul_f32_e32 v16, 0x43000000, v26
	v_mul_f32_e32 v17, 0x43000000, v30
	v_med3_f32 v16, v16, s13, v149
	v_med3_f32 v17, v17, s13, v149
	v_mov_b32_e32 v20, 0
	v_cvt_pk_fp8_f32 v20, v16, v17
	v_mul_f32_e32 v16, 0x43000000, v18
	v_mul_f32_e32 v17, 0x43000000, v22
	v_med3_f32 v16, v16, s13, v149
	v_med3_f32 v17, v17, s13, v149
	v_cvt_pk_fp8_f32 v20, v16, v17 op_sel:[0,0,1]
	v_mul_f32_e32 v16, 0x43000000, v27
	v_mul_f32_e32 v17, 0x43000000, v31
	v_med3_f32 v16, v16, s13, v149
	v_med3_f32 v17, v17, s13, v149
	v_mov_b32_e32 v18, 0
	v_cvt_pk_fp8_f32 v18, v16, v17
	v_mul_f32_e32 v16, 0x43000000, v19
	v_mul_f32_e32 v17, 0x43000000, v23
	v_med3_f32 v16, v16, s13, v149
	v_med3_f32 v17, v17, s13, v149
	s_waitcnt vmcnt(3)
	v_mul_f32_e32 v8, 0x43000000, v8
	s_waitcnt vmcnt(2)
	v_mul_f32_e32 v12, 0x43000000, v12
	v_cvt_pk_fp8_f32 v18, v16, v17 op_sel:[0,0,1]
	v_med3_f32 v8, v8, s13, v149
	v_med3_f32 v12, v12, s13, v149
	v_mov_b32_e32 v16, 0
	v_cvt_pk_fp8_f32 v16, v8, v12
	s_waitcnt vmcnt(1)
	v_mul_f32_e32 v0, 0x43000000, v0
	s_waitcnt vmcnt(0)
	v_mul_f32_e32 v4, 0x43000000, v4
	v_med3_f32 v0, v0, s13, v149
	v_med3_f32 v4, v4, s13, v149
	v_cvt_pk_fp8_f32 v16, v0, v4 op_sel:[0,0,1]
	v_mul_f32_e32 v0, 0x43000000, v9
	v_mul_f32_e32 v4, 0x43000000, v13
	v_med3_f32 v0, v0, s13, v149
	v_med3_f32 v4, v4, s13, v149
	v_mov_b32_e32 v8, 0
	v_cvt_pk_fp8_f32 v8, v0, v4
	v_mul_f32_e32 v0, 0x43000000, v1
	v_mul_f32_e32 v1, 0x43000000, v5
	v_med3_f32 v0, v0, s13, v149
	v_med3_f32 v1, v1, s13, v149
	v_cvt_pk_fp8_f32 v8, v0, v1 op_sel:[0,0,1]
	v_mul_f32_e32 v0, 0x43000000, v10
	v_mul_f32_e32 v1, 0x43000000, v14
	v_med3_f32 v0, v0, s13, v149
	v_med3_f32 v1, v1, s13, v149
	v_mov_b32_e32 v4, 0
	v_cvt_pk_fp8_f32 v4, v0, v1
	v_mul_f32_e32 v0, 0x43000000, v2
	v_mul_f32_e32 v1, 0x43000000, v6
	v_med3_f32 v0, v0, s13, v149
	v_med3_f32 v1, v1, s13, v149
	v_cvt_pk_fp8_f32 v4, v0, v1 op_sel:[0,0,1]
	v_mul_f32_e32 v0, 0x43000000, v11
	v_mul_f32_e32 v1, 0x43000000, v15
	v_med3_f32 v0, v0, s13, v149
	v_med3_f32 v1, v1, s13, v149
	v_mov_b32_e32 v2, 0
	v_cvt_pk_fp8_f32 v2, v0, v1
	v_mul_f32_e32 v0, 0x43000000, v3
	v_mul_f32_e32 v1, 0x43000000, v7
	v_med3_f32 v0, v0, s13, v149
	v_med3_f32 v1, v1, s13, v149
	v_cvt_pk_fp8_f32 v2, v0, v1 op_sel:[0,0,1]
	ds_write2_b32 v150, v158, v120 offset1:32
	ds_write2_b32 v150, v116, v114 offset0:64 offset1:96
	ds_write2_b32 v151, v112, v104 offset1:32
	ds_write2_b32 v151, v100, v98 offset0:64 offset1:96
	ds_write2_b32 v152, v96, v88 offset1:32
	ds_write2_b32 v152, v84, v82 offset0:64 offset1:96
	ds_write2_b32 v153, v80, v72 offset1:32
	ds_write2_b32 v153, v68, v66 offset0:64 offset1:96
	ds_write2_b32 v154, v64, v56 offset1:32
	ds_write2_b32 v154, v52, v50 offset0:64 offset1:96
	ds_write2_b32 v155, v48, v40 offset1:32
	ds_write2_b32 v155, v36, v34 offset0:64 offset1:96
	ds_write2_b32 v156, v32, v24 offset1:32
	ds_write2_b32 v156, v20, v18 offset0:64 offset1:96
	ds_write2_b32 v157, v16, v8 offset1:32
	ds_write2_b32 v157, v4, v2 offset0:64 offset1:96
	s_waitcnt lgkmcnt(0)
	ds_read_b128 v[0:3], v134
	v_lshl_add_u64 v[4:5], v[130:131], 0, s[4:5]
	v_add_u32_e32 v6, s2, v133
	v_mad_i64_i32 v[6:7], s[4:5], v6, s14, v[4:5]
	s_waitcnt lgkmcnt(0)
	global_store_dwordx4 v[6:7], v[0:3], off
	ds_read_b128 v[0:3], v136
	v_add_u32_e32 v6, s2, v135
	v_mad_i64_i32 v[6:7], s[4:5], v6, s14, v[4:5]
	s_waitcnt lgkmcnt(0)
	global_store_dwordx4 v[6:7], v[0:3], off
	ds_read_b128 v[0:3], v138
	v_add_u32_e32 v6, s2, v137
	v_mad_i64_i32 v[6:7], s[4:5], v6, s14, v[4:5]
	s_waitcnt lgkmcnt(0)
	global_store_dwordx4 v[6:7], v[0:3], off
	ds_read_b128 v[0:3], v140
	v_add_u32_e32 v6, s2, v139
	v_mad_i64_i32 v[6:7], s[4:5], v6, s14, v[4:5]
	s_waitcnt lgkmcnt(0)
	global_store_dwordx4 v[6:7], v[0:3], off
	ds_read_b128 v[0:3], v142
	v_add_u32_e32 v6, s2, v141
	v_mad_i64_i32 v[6:7], s[4:5], v6, s14, v[4:5]
	s_waitcnt lgkmcnt(0)
	global_store_dwordx4 v[6:7], v[0:3], off
	ds_read_b128 v[0:3], v144
	v_add_u32_e32 v6, s2, v143
	v_mad_i64_i32 v[6:7], s[4:5], v6, s14, v[4:5]
	s_waitcnt lgkmcnt(0)
	global_store_dwordx4 v[6:7], v[0:3], off
	ds_read_b128 v[0:3], v146
	v_add_u32_e32 v6, s2, v145
	v_mad_i64_i32 v[6:7], s[4:5], v6, s14, v[4:5]
	s_waitcnt lgkmcnt(0)
	global_store_dwordx4 v[6:7], v[0:3], off
	ds_read_b128 v[0:3], v148
	v_add_u32_e32 v6, s2, v147
	v_mad_i64_i32 v[4:5], s[4:5], v6, s14, v[4:5]
	s_waitcnt lgkmcnt(0)
	global_store_dwordx4 v[4:5], v[0:3], off
	s_waitcnt lgkmcnt(0)
	s_cbranch_scc1 .LBB0_232

.LBB0_1575:
	s_and_b32 s4, s6, 0xffffff80
	v_add_u32_e32 v0, s4, v64
	v_ashrrev_i32_e32 v1, 31, v0
	s_and_b32 s12, s8, 0xfc0
	v_lshlrev_b64 v[0:1], 14, v[0:1]
	s_lshl_b32 s0, s12, 2
	v_lshl_add_u64 v[0:1], s[56:57], 0, v[0:1]
	s_ashr_i32 s5, s4, 31
	v_lshl_add_u64 v[0:1], v[0:1], 0, s[0:1]
	v_add_u32_e32 v4, s12, v65
	v_add_u32_e32 v5, s12, v67
	v_add_u32_e32 v6, s12, v69
	v_add_u32_e32 v7, s12, v71
	v_add_u32_e32 v8, s12, v73
	v_add_u32_e32 v9, s12, v75
	v_add_u32_e32 v10, s12, v77
	v_add_u32_e32 v11, s12, v79
	v_lshl_add_u64 v[2:3], v[46:47], 0, s[4:5]
	v_lshl_add_u64 v[0:1], v[0:1], 0, v[44:45]
	v_mad_i64_i32 v[48:49], s[4:5], v4, s11, v[2:3]
	v_mad_i64_i32 v[50:51], s[4:5], v5, s11, v[2:3]
	v_mad_i64_i32 v[52:53], s[4:5], v6, s11, v[2:3]
	v_mad_i64_i32 v[54:55], s[4:5], v7, s11, v[2:3]
	v_mad_i64_i32 v[56:57], s[4:5], v8, s11, v[2:3]
	v_mad_i64_i32 v[58:59], s[4:5], v9, s11, v[2:3]
	v_mad_i64_i32 v[60:61], s[4:5], v10, s11, v[2:3]
	v_mad_i64_i32 v[62:63], s[4:5], v11, s11, v[2:3]
	v_add_co_u32_e32 v2, vcc, 0x4000, v0
	global_load_dwordx4 v[122:125], v[0:1], off nt
	s_nop 0
	v_addc_co_u32_e32 v3, vcc, 0, v1, vcc
	v_add_co_u32_e32 v4, vcc, 0x8000, v0
	s_nop 1
	global_load_dwordx4 v[126:129], v[2:3], off nt
	s_nop 0
	v_addc_co_u32_e32 v5, vcc, 0, v1, vcc
	v_add_co_u32_e32 v2, vcc, 0xc000, v0
	s_nop 1
	s_nop 0
	v_addc_co_u32_e32 v3, vcc, 0, v1, vcc
	v_add_co_u32_e32 v6, vcc, 0x40000, v0
	s_nop 1
	global_load_dwordx4 v[130:133], v[4:5], off nt
	global_load_dwordx4 v[134:137], v[2:3], off nt
	v_addc_co_u32_e32 v7, vcc, 0, v1, vcc
	v_add_co_u32_e32 v2, vcc, 0x44000, v0
	s_nop 1
	v_addc_co_u32_e32 v3, vcc, 0, v1, vcc
	v_add_co_u32_e32 v4, vcc, 0x48000, v0
	s_nop 1
	global_load_dwordx4 v[138:141], v[6:7], off nt
	global_load_dwordx4 v[142:145], v[2:3], off nt
	v_addc_co_u32_e32 v5, vcc, 0, v1, vcc
	v_add_co_u32_e32 v2, vcc, 0x4c000, v0
	s_nop 1
	s_nop 0
	v_addc_co_u32_e32 v3, vcc, 0, v1, vcc
	v_add_co_u32_e32 v6, vcc, 0x80000, v0
	s_nop 1
	global_load_dwordx4 v[146:149], v[4:5], off nt
	global_load_dwordx4 v[150:153], v[2:3], off nt
	v_addc_co_u32_e32 v7, vcc, 0, v1, vcc
	v_add_co_u32_e32 v2, vcc, 0x84000, v0
	s_nop 1
	v_addc_co_u32_e32 v3, vcc, 0, v1, vcc
	v_add_co_u32_e32 v4, vcc, 0x88000, v0
	s_nop 1
	global_load_dwordx4 v[154:157], v[6:7], off nt
	global_load_dwordx4 v[158:161], v[2:3], off nt
	v_addc_co_u32_e32 v5, vcc, 0, v1, vcc
	v_add_co_u32_e32 v2, vcc, 0x8c000, v0
	s_nop 1
	s_nop 0
	v_addc_co_u32_e32 v3, vcc, 0, v1, vcc
	v_add_co_u32_e32 v6, vcc, 0xc0000, v0
	s_nop 1
	global_load_dwordx4 v[162:165], v[4:5], off nt
	global_load_dwordx4 v[166:169], v[2:3], off nt
	v_addc_co_u32_e32 v7, vcc, 0, v1, vcc
	v_add_co_u32_e32 v2, vcc, 0xc4000, v0
	s_nop 1
	s_nop 0
	v_addc_co_u32_e32 v3, vcc, 0, v1, vcc
	v_add_co_u32_e32 v4, vcc, 0xc8000, v0
	s_nop 1
	global_load_dwordx4 v[170:173], v[6:7], off nt
	global_load_dwordx4 v[174:177], v[2:3], off nt
	v_addc_co_u32_e32 v5, vcc, 0, v1, vcc
	v_add_co_u32_e32 v2, vcc, 0xcc000, v0
	s_nop 1
	v_addc_co_u32_e32 v3, vcc, 0, v1, vcc
	v_add_co_u32_e32 v6, vcc, 0x100000, v0
	s_nop 1
	global_load_dwordx4 v[178:181], v[4:5], off nt
	global_load_dwordx4 v[182:185], v[2:3], off nt
	v_addc_co_u32_e32 v7, vcc, 0, v1, vcc
	v_add_co_u32_e32 v2, vcc, 0x104000, v0
	s_nop 1
	v_addc_co_u32_e32 v3, vcc, 0, v1, vcc
	v_add_co_u32_e32 v4, vcc, 0x108000, v0
	s_nop 1
	global_load_dwordx4 v[186:189], v[6:7], off nt
	global_load_dwordx4 v[190:193], v[2:3], off nt
	v_addc_co_u32_e32 v5, vcc, 0, v1, vcc
	v_add_co_u32_e32 v2, vcc, 0x10c000, v0
	s_nop 1
	s_nop 0
	v_addc_co_u32_e32 v3, vcc, 0, v1, vcc
	v_add_co_u32_e32 v6, vcc, 0x140000, v0
	s_nop 1
	global_load_dwordx4 v[194:197], v[4:5], off nt
	global_load_dwordx4 v[198:201], v[2:3], off nt
	v_addc_co_u32_e32 v7, vcc, 0, v1, vcc
	v_add_co_u32_e32 v2, vcc, 0x144000, v0
	s_nop 1
	v_addc_co_u32_e32 v3, vcc, 0, v1, vcc
	v_add_co_u32_e32 v4, vcc, 0x148000, v0
	s_nop 1
	global_load_dwordx4 v[202:205], v[6:7], off nt
	global_load_dwordx4 v[40:43], v[2:3], off nt
	v_addc_co_u32_e32 v5, vcc, 0, v1, vcc
	v_add_co_u32_e32 v2, vcc, 0x14c000, v0
	s_nop 1
	s_nop 0
	v_addc_co_u32_e32 v3, vcc, 0, v1, vcc
	v_add_co_u32_e32 v6, vcc, 0x180000, v0
	s_nop 1
	global_load_dwordx4 v[36:39], v[4:5], off nt
	global_load_dwordx4 v[32:35], v[2:3], off nt
	v_addc_co_u32_e32 v7, vcc, 0, v1, vcc
	v_add_co_u32_e32 v2, vcc, 0x184000, v0
	s_nop 1
	s_nop 0
	v_addc_co_u32_e32 v3, vcc, 0, v1, vcc
	v_add_co_u32_e32 v4, vcc, 0x188000, v0
	s_nop 1
	global_load_dwordx4 v[28:31], v[6:7], off nt
	global_load_dwordx4 v[24:27], v[2:3], off nt
	v_addc_co_u32_e32 v5, vcc, 0, v1, vcc
	v_add_co_u32_e32 v2, vcc, 0x18c000, v0
	s_nop 1
	s_nop 0
	v_addc_co_u32_e32 v3, vcc, 0, v1, vcc
	v_add_co_u32_e32 v6, vcc, 0x1c0000, v0
	s_nop 1
	global_load_dwordx4 v[20:23], v[4:5], off nt
	global_load_dwordx4 v[16:19], v[2:3], off nt
	v_addc_co_u32_e32 v7, vcc, 0, v1, vcc
	v_add_co_u32_e32 v2, vcc, 0x1c4000, v0
	s_nop 1
	s_nop 0
	v_addc_co_u32_e32 v3, vcc, 0, v1, vcc
	v_add_co_u32_e32 v4, vcc, 0x1c8000, v0
	s_nop 1
	global_load_dwordx4 v[12:15], v[6:7], off nt
	global_load_dwordx4 v[8:11], v[2:3], off nt
	v_addc_co_u32_e32 v5, vcc, 0, v1, vcc
	v_add_co_u32_e32 v0, vcc, 0x1cc000, v0
	s_nop 1
	s_nop 0
	v_addc_co_u32_e32 v1, vcc, 0, v1, vcc
	global_load_dwordx4 v[4:7], v[4:5], off nt
	s_nop 0
	global_load_dwordx4 v[0:3], v[0:1], off nt
	v_mov_b32_e32 v90, 0
	v_mov_b32_e32 v92, 0
	v_mov_b32_e32 v95, 0
	v_mov_b32_e32 v100, 0
	v_mov_b32_e32 v91, 0
	v_mov_b32_e32 v94, 0
	v_mov_b32_e32 v104, 0
	s_waitcnt vmcnt(31)
	v_mul_f32_e32 v122, 0x43000000, v122
	v_mul_f32_e32 v123, 0x43000000, v123
	s_waitcnt vmcnt(30)
	v_mul_f32_e32 v126, 0x43000000, v126
	v_mul_f32_e32 v127, 0x43000000, v127
	v_mul_f32_e32 v124, 0x43000000, v124
	v_mul_f32_e32 v125, 0x43000000, v125
	v_med3_f32 v122, v122, s10, v81
	v_med3_f32 v123, v123, s10, v81
	v_mul_f32_e32 v128, 0x43000000, v128
	v_mul_f32_e32 v129, 0x43000000, v129
	v_med3_f32 v126, v126, s10, v81
	v_med3_f32 v127, v127, s10, v81
	v_med3_f32 v124, v124, s10, v81
	v_med3_f32 v125, v125, s10, v81
	v_med3_f32 v128, v128, s10, v81
	v_med3_f32 v129, v129, s10, v81
	v_cvt_pk_fp8_f32 v90, v122, v126
	v_cvt_pk_fp8_f32 v92, v123, v127
	s_waitcnt vmcnt(29)
	v_mul_f32_e32 v130, 0x43000000, v130
	v_mul_f32_e32 v131, 0x43000000, v131
	v_mul_f32_e32 v133, 0x43000000, v133
	v_cvt_pk_fp8_f32 v95, v124, v128
	v_cvt_pk_fp8_f32 v100, v125, v129
	v_mul_f32_e32 v132, 0x43000000, v132
	v_med3_f32 v122, v130, s10, v81
	s_waitcnt vmcnt(28)
	v_mul_f32_e32 v126, 0x43000000, v134
	v_med3_f32 v123, v131, s10, v81
	v_mul_f32_e32 v127, 0x43000000, v135
	v_med3_f32 v125, v133, s10, v81
	v_mul_f32_e32 v129, 0x43000000, v137
	s_waitcnt vmcnt(27)
	v_mul_f32_e32 v130, 0x43000000, v138
	v_mul_f32_e32 v131, 0x43000000, v139
	v_mul_f32_e32 v133, 0x43000000, v141
	s_waitcnt vmcnt(26)
	v_mul_f32_e32 v134, 0x43000000, v142
	v_mul_f32_e32 v135, 0x43000000, v143
	v_mul_f32_e32 v137, 0x43000000, v145
	v_med3_f32 v124, v132, s10, v81
	v_mul_f32_e32 v128, 0x43000000, v136
	v_med3_f32 v126, v126, s10, v81
	v_med3_f32 v127, v127, s10, v81
	v_mul_f32_e32 v132, 0x43000000, v140
	v_med3_f32 v130, v130, s10, v81
	v_med3_f32 v131, v131, s10, v81
	v_mul_f32_e32 v136, 0x43000000, v144
	v_med3_f32 v133, v133, s10, v81
	v_med3_f32 v134, v134, s10, v81
	v_med3_f32 v135, v135, s10, v81
	v_med3_f32 v137, v137, s10, v81
	v_mov_b32_e32 v98, 0
	v_med3_f32 v128, v128, s10, v81
	v_med3_f32 v129, v129, s10, v81
	v_med3_f32 v132, v132, s10, v81
	v_med3_f32 v136, v136, s10, v81
	v_cvt_pk_fp8_f32 v90, v122, v126 op_sel:[0,0,1]
	v_cvt_pk_fp8_f32 v92, v123, v127 op_sel:[0,0,1]
	v_cvt_pk_fp8_f32 v91, v130, v134
	v_cvt_pk_fp8_f32 v94, v131, v135
	v_cvt_pk_fp8_f32 v104, v133, v137
	s_waitcnt vmcnt(23)
	v_mul_f32_e32 v130, 0x43000000, v154
	v_mul_f32_e32 v131, 0x43000000, v155
	s_waitcnt vmcnt(22)
	v_mul_f32_e32 v134, 0x43000000, v158
	v_mul_f32_e32 v135, 0x43000000, v159
	v_mov_b32_e32 v93, 0
	v_mov_b32_e32 v97, 0
	v_cvt_pk_fp8_f32 v95, v124, v128 op_sel:[0,0,1]
	v_cvt_pk_fp8_f32 v100, v125, v129 op_sel:[0,0,1]
	v_cvt_pk_fp8_f32 v98, v132, v136
	v_mul_f32_e32 v132, 0x43000000, v156
	v_mul_f32_e32 v133, 0x43000000, v157
	v_med3_f32 v130, v130, s10, v81
	v_med3_f32 v131, v131, s10, v81
	v_mul_f32_e32 v136, 0x43000000, v160
	v_mul_f32_e32 v137, 0x43000000, v161
	v_med3_f32 v134, v134, s10, v81
	v_med3_f32 v135, v135, s10, v81
	v_mov_b32_e32 v102, 0
	v_mov_b32_e32 v107, 0
	v_mul_f32_e32 v138, 0x43000000, v146
	v_mul_f32_e32 v139, 0x43000000, v147
	v_mul_f32_e32 v141, 0x43000000, v149
	v_mul_f32_e32 v123, 0x43000000, v150
	v_mul_f32_e32 v125, 0x43000000, v151
	v_mul_f32_e32 v129, 0x43000000, v153
	v_med3_f32 v132, v132, s10, v81
	v_med3_f32 v133, v133, s10, v81
	v_med3_f32 v136, v136, s10, v81
	v_med3_f32 v137, v137, s10, v81
	v_cvt_pk_fp8_f32 v93, v130, v134
	v_cvt_pk_fp8_f32 v97, v131, v135
	v_mul_f32_e32 v140, 0x43000000, v148
	v_med3_f32 v122, v138, s10, v81
	v_med3_f32 v124, v139, s10, v81
	v_mul_f32_e32 v127, 0x43000000, v152
	v_med3_f32 v128, v141, s10, v81
	v_med3_f32 v123, v123, s10, v81
	v_med3_f32 v125, v125, s10, v81
	v_med3_f32 v129, v129, s10, v81
	v_cvt_pk_fp8_f32 v102, v132, v136
	v_cvt_pk_fp8_f32 v107, v133, v137
	v_med3_f32 v126, v140, s10, v81
	v_med3_f32 v127, v127, s10, v81
	s_waitcnt vmcnt(21)
	v_mul_f32_e32 v138, 0x43000000, v162
	v_mul_f32_e32 v139, 0x43000000, v163
	ds_write2_b32 v82, v90, v92 offset1:32
	ds_write2_b32 v82, v95, v100 offset0:64 offset1:96
	v_cvt_pk_fp8_f32 v91, v122, v123 op_sel:[0,0,1]
	v_cvt_pk_fp8_f32 v94, v124, v125 op_sel:[0,0,1]
	v_cvt_pk_fp8_f32 v104, v128, v129 op_sel:[0,0,1]
	s_waitcnt vmcnt(20)
	v_mul_f32_e32 v92, 0x43000000, v166
	v_mul_f32_e32 v100, 0x43000000, v167
	s_waitcnt vmcnt(19)
	v_mul_f32_e32 v129, 0x43000000, v173
	s_waitcnt vmcnt(18)
	v_mul_f32_e32 v133, 0x43000000, v177
	v_mov_b32_e32 v110, 0
	v_mul_f32_e32 v140, 0x43000000, v164
	v_mul_f32_e32 v141, 0x43000000, v165
	v_cvt_pk_fp8_f32 v98, v126, v127 op_sel:[0,0,1]
	v_med3_f32 v90, v138, s10, v81
	v_med3_f32 v95, v139, s10, v81
	v_mul_f32_e32 v123, 0x43000000, v168
	v_mul_f32_e32 v125, 0x43000000, v169
	v_med3_f32 v92, v92, s10, v81
	v_med3_f32 v100, v100, s10, v81
	v_med3_f32 v129, v129, s10, v81
	v_med3_f32 v133, v133, s10, v81
	v_med3_f32 v122, v140, s10, v81
	v_med3_f32 v124, v141, s10, v81
	v_med3_f32 v123, v123, s10, v81
	v_med3_f32 v125, v125, s10, v81
	v_cvt_pk_fp8_f32 v93, v90, v92 op_sel:[0,0,1]
	v_cvt_pk_fp8_f32 v97, v95, v100 op_sel:[0,0,1]
	v_cvt_pk_fp8_f32 v110, v129, v133
	v_cvt_pk_fp8_f32 v102, v122, v123 op_sel:[0,0,1]
	v_cvt_pk_fp8_f32 v107, v124, v125 op_sel:[0,0,1]
	v_mul_f32_e32 v126, 0x43000000, v170
	v_mul_f32_e32 v127, 0x43000000, v171
	v_mul_f32_e32 v130, 0x43000000, v174
	v_mul_f32_e32 v131, 0x43000000, v175
	s_waitcnt vmcnt(17)
	v_mul_f32_e32 v137, 0x43000000, v181
	ds_write2_b32 v83, v91, v94 offset1:32
	ds_write2_b32 v83, v98, v104 offset0:64 offset1:96
	s_waitcnt vmcnt(16)
	v_mul_f32_e32 v104, 0x43000000, v185
	v_mov_b32_e32 v96, 0
	v_mov_b32_e32 v101, 0
	v_mul_f32_e32 v128, 0x43000000, v172
	v_med3_f32 v126, v126, s10, v81
	v_med3_f32 v127, v127, s10, v81
	v_mul_f32_e32 v132, 0x43000000, v176
	v_med3_f32 v130, v130, s10, v81
	v_med3_f32 v131, v131, s10, v81
	v_med3_f32 v100, v137, s10, v81
	v_med3_f32 v104, v104, s10, v81
	v_mov_b32_e32 v106, 0
	v_med3_f32 v128, v128, s10, v81
	v_med3_f32 v132, v132, s10, v81
	v_cvt_pk_fp8_f32 v96, v126, v130
	v_cvt_pk_fp8_f32 v101, v127, v131
	s_waitcnt vmcnt(15)
	v_mul_f32_e32 v122, 0x43000000, v186
	v_mul_f32_e32 v123, 0x43000000, v187
	s_waitcnt vmcnt(14)
	v_mul_f32_e32 v126, 0x43000000, v190
	v_mul_f32_e32 v127, 0x43000000, v191
	ds_write2_b32 v84, v93, v97 offset1:32
	ds_write2_b32 v84, v102, v107 offset0:64 offset1:96
	v_cvt_pk_fp8_f32 v110, v100, v104 op_sel:[0,0,1]
	s_waitcnt vmcnt(11)
	v_mul_f32_e32 v100, 0x43000000, v202
	v_mul_f32_e32 v102, 0x43000000, v203
	s_waitcnt vmcnt(10)
	v_mul_f32_e32 v40, 0x43000000, v40
	v_mul_f32_e32 v41, 0x43000000, v41
	s_waitcnt vmcnt(7)
	v_mul_f32_e32 v28, 0x43000000, v28
	v_mul_f32_e32 v29, 0x43000000, v29
	s_waitcnt vmcnt(6)
	v_mul_f32_e32 v24, 0x43000000, v24
	v_mul_f32_e32 v25, 0x43000000, v25
	v_mov_b32_e32 v99, 0
	v_mov_b32_e32 v105, 0
	v_mov_b32_e32 v103, 0
	v_mov_b32_e32 v108, 0
	v_mov_b32_e32 v112, 0
	v_mov_b32_e32 v115, 0
	v_cvt_pk_fp8_f32 v106, v128, v132
	v_mul_f32_e32 v124, 0x43000000, v188
	v_mul_f32_e32 v125, 0x43000000, v189
	v_med3_f32 v122, v122, s10, v81
	v_med3_f32 v123, v123, s10, v81
	v_mul_f32_e32 v128, 0x43000000, v192
	v_mul_f32_e32 v129, 0x43000000, v193
	v_med3_f32 v126, v126, s10, v81
	v_med3_f32 v127, v127, s10, v81
	v_mul_f32_e32 v104, 0x43000000, v204
	v_mul_f32_e32 v107, 0x43000000, v205
	v_med3_f32 v100, v100, s10, v81
	v_med3_f32 v102, v102, s10, v81
	v_mul_f32_e32 v42, 0x43000000, v42
	v_mul_f32_e32 v43, 0x43000000, v43
	v_med3_f32 v40, v40, s10, v81
	v_med3_f32 v41, v41, s10, v81
	v_mul_f32_e32 v30, 0x43000000, v30
	v_mul_f32_e32 v31, 0x43000000, v31
	v_med3_f32 v28, v28, s10, v81
	v_med3_f32 v29, v29, s10, v81
	v_mul_f32_e32 v26, 0x43000000, v26
	v_mul_f32_e32 v27, 0x43000000, v27
	v_med3_f32 v24, v24, s10, v81
	v_med3_f32 v25, v25, s10, v81
	v_mov_b32_e32 v109, 0
	v_mov_b32_e32 v113, 0
	v_mov_b32_e32 v111, 0
	v_mov_b32_e32 v114, 0
	v_mov_b32_e32 v116, 0
	v_mov_b32_e32 v117, 0
	v_mul_f32_e32 v134, 0x43000000, v178
	v_mul_f32_e32 v91, 0x43000000, v182
	v_med3_f32 v124, v124, s10, v81
	v_med3_f32 v125, v125, s10, v81
	v_med3_f32 v128, v128, s10, v81
	v_med3_f32 v129, v129, s10, v81
	v_cvt_pk_fp8_f32 v99, v122, v126
	v_cvt_pk_fp8_f32 v105, v123, v127
	v_med3_f32 v104, v104, s10, v81
	v_med3_f32 v107, v107, s10, v81
	v_med3_f32 v42, v42, s10, v81
	v_med3_f32 v43, v43, s10, v81
	v_cvt_pk_fp8_f32 v103, v100, v40
	v_cvt_pk_fp8_f32 v108, v102, v41
	v_med3_f32 v30, v30, s10, v81
	v_med3_f32 v31, v31, s10, v81
	v_med3_f32 v26, v26, s10, v81
	v_med3_f32 v27, v27, s10, v81
	v_cvt_pk_fp8_f32 v112, v28, v24
	v_cvt_pk_fp8_f32 v115, v29, v25
	s_waitcnt vmcnt(3)
	v_mul_f32_e32 v12, 0x43000000, v12
	v_mul_f32_e32 v13, 0x43000000, v13
	s_waitcnt vmcnt(2)
	v_mul_f32_e32 v8, 0x43000000, v8
	v_mul_f32_e32 v9, 0x43000000, v9
	v_mov_b32_e32 v118, 0
	v_mov_b32_e32 v119, 0
	v_mul_f32_e32 v135, 0x43000000, v179
	v_mul_f32_e32 v136, 0x43000000, v180
	v_med3_f32 v90, v134, s10, v81
	v_mul_f32_e32 v94, 0x43000000, v183
	v_mul_f32_e32 v98, 0x43000000, v184
	v_med3_f32 v91, v91, s10, v81
	v_cvt_pk_fp8_f32 v109, v124, v128
	v_cvt_pk_fp8_f32 v113, v125, v129
	v_cvt_pk_fp8_f32 v111, v104, v42
	v_cvt_pk_fp8_f32 v114, v107, v43
	v_cvt_pk_fp8_f32 v116, v30, v26
	v_cvt_pk_fp8_f32 v117, v31, v27
	v_mul_f32_e32 v14, 0x43000000, v14
	v_mul_f32_e32 v15, 0x43000000, v15
	v_med3_f32 v12, v12, s10, v81
	v_med3_f32 v13, v13, s10, v81
	v_mul_f32_e32 v10, 0x43000000, v10
	v_mul_f32_e32 v11, 0x43000000, v11
	v_med3_f32 v8, v8, s10, v81
	v_med3_f32 v9, v9, s10, v81
	v_mov_b32_e32 v120, 0
	v_mov_b32_e32 v121, 0
	v_med3_f32 v92, v135, s10, v81
	v_med3_f32 v95, v136, s10, v81
	v_med3_f32 v94, v94, s10, v81
	v_med3_f32 v98, v98, s10, v81
	v_mul_f32_e32 v130, 0x43000000, v194
	v_mul_f32_e32 v131, 0x43000000, v195
	v_cvt_pk_fp8_f32 v96, v90, v91 op_sel:[0,0,1]
	v_mul_f32_e32 v91, 0x43000000, v198
	v_mul_f32_e32 v93, 0x43000000, v199
	v_mul_f32_e32 v36, 0x43000000, v36
	v_mul_f32_e32 v37, 0x43000000, v37
	v_mul_f32_e32 v32, 0x43000000, v32
	v_mul_f32_e32 v33, 0x43000000, v33
	v_mul_f32_e32 v20, 0x43000000, v20
	v_mul_f32_e32 v21, 0x43000000, v21
	v_mul_f32_e32 v16, 0x43000000, v16
	v_mul_f32_e32 v17, 0x43000000, v17
	v_med3_f32 v14, v14, s10, v81
	v_med3_f32 v15, v15, s10, v81
	v_med3_f32 v10, v10, s10, v81
	v_med3_f32 v11, v11, s10, v81
	v_cvt_pk_fp8_f32 v118, v12, v8
	v_cvt_pk_fp8_f32 v119, v13, v9
	v_mul_f32_e32 v132, 0x43000000, v196
	v_mul_f32_e32 v133, 0x43000000, v197
	v_cvt_pk_fp8_f32 v101, v92, v94 op_sel:[0,0,1]
	v_cvt_pk_fp8_f32 v106, v95, v98 op_sel:[0,0,1]
	v_med3_f32 v90, v130, s10, v81
	v_med3_f32 v92, v131, s10, v81
	v_mul_f32_e32 v95, 0x43000000, v200
	v_mul_f32_e32 v98, 0x43000000, v201
	v_med3_f32 v91, v91, s10, v81
	v_med3_f32 v93, v93, s10, v81
	v_mul_f32_e32 v38, 0x43000000, v38
	v_mul_f32_e32 v39, 0x43000000, v39
	v_med3_f32 v36, v36, s10, v81
	v_med3_f32 v37, v37, s10, v81
	v_mul_f32_e32 v34, 0x43000000, v34
	v_mul_f32_e32 v35, 0x43000000, v35
	v_med3_f32 v32, v32, s10, v81
	v_med3_f32 v33, v33, s10, v81
	v_mul_f32_e32 v22, 0x43000000, v22
	v_mul_f32_e32 v23, 0x43000000, v23
	v_med3_f32 v20, v20, s10, v81
	v_med3_f32 v21, v21, s10, v81
	v_mul_f32_e32 v18, 0x43000000, v18
	v_mul_f32_e32 v19, 0x43000000, v19
	v_med3_f32 v16, v16, s10, v81
	v_med3_f32 v17, v17, s10, v81
	v_cvt_pk_fp8_f32 v120, v14, v10
	v_cvt_pk_fp8_f32 v121, v15, v11
	v_med3_f32 v94, v132, s10, v81
	v_med3_f32 v97, v133, s10, v81
	v_med3_f32 v95, v95, s10, v81
	v_med3_f32 v98, v98, s10, v81
	v_cvt_pk_fp8_f32 v99, v90, v91 op_sel:[0,0,1]
	v_cvt_pk_fp8_f32 v105, v92, v93 op_sel:[0,0,1]
	v_med3_f32 v38, v38, s10, v81
	v_med3_f32 v39, v39, s10, v81
	v_med3_f32 v34, v34, s10, v81
	v_med3_f32 v35, v35, s10, v81
	v_cvt_pk_fp8_f32 v103, v36, v32 op_sel:[0,0,1]
	v_cvt_pk_fp8_f32 v108, v37, v33 op_sel:[0,0,1]
	v_med3_f32 v22, v22, s10, v81
	v_med3_f32 v23, v23, s10, v81
	v_med3_f32 v18, v18, s10, v81
	v_med3_f32 v19, v19, s10, v81
	s_waitcnt vmcnt(1)
	v_mul_f32_e32 v4, 0x43000000, v4
	v_mul_f32_e32 v5, 0x43000000, v5
	v_cvt_pk_fp8_f32 v112, v20, v16 op_sel:[0,0,1]
	v_cvt_pk_fp8_f32 v115, v21, v17 op_sel:[0,0,1]
	s_waitcnt vmcnt(0)
	v_mul_f32_e32 v0, 0x43000000, v0
	v_mul_f32_e32 v1, 0x43000000, v1
	v_cvt_pk_fp8_f32 v109, v94, v95 op_sel:[0,0,1]
	v_cvt_pk_fp8_f32 v113, v97, v98 op_sel:[0,0,1]
	v_cvt_pk_fp8_f32 v111, v38, v34 op_sel:[0,0,1]
	v_cvt_pk_fp8_f32 v114, v39, v35 op_sel:[0,0,1]
	v_mul_f32_e32 v6, 0x43000000, v6
	v_mul_f32_e32 v7, 0x43000000, v7
	v_cvt_pk_fp8_f32 v116, v22, v18 op_sel:[0,0,1]
	v_cvt_pk_fp8_f32 v117, v23, v19 op_sel:[0,0,1]
	v_med3_f32 v4, v4, s10, v81
	v_med3_f32 v5, v5, s10, v81
	v_mul_f32_e32 v2, 0x43000000, v2
	v_mul_f32_e32 v3, 0x43000000, v3
	v_med3_f32 v0, v0, s10, v81
	v_med3_f32 v1, v1, s10, v81
	v_med3_f32 v6, v6, s10, v81
	v_med3_f32 v7, v7, s10, v81
	v_med3_f32 v2, v2, s10, v81
	v_med3_f32 v3, v3, s10, v81
	v_cvt_pk_fp8_f32 v118, v4, v0 op_sel:[0,0,1]
	v_cvt_pk_fp8_f32 v119, v5, v1 op_sel:[0,0,1]
	v_cvt_pk_fp8_f32 v120, v6, v2 op_sel:[0,0,1]
	v_cvt_pk_fp8_f32 v121, v7, v3 op_sel:[0,0,1]
	ds_write2_b32 v85, v96, v101 offset1:32
	ds_write2_b32 v85, v106, v110 offset0:64 offset1:96
	ds_write2_b32 v86, v99, v105 offset1:32
	ds_write2_b32 v86, v109, v113 offset0:64 offset1:96
	ds_write2_b32 v87, v103, v108 offset1:32
	ds_write2_b32 v87, v111, v114 offset0:64 offset1:96
	ds_write2_b32 v88, v112, v115 offset1:32
	ds_write2_b32 v88, v116, v117 offset0:64 offset1:96
	ds_write2_b32 v89, v118, v119 offset1:32
	ds_write2_b32 v89, v120, v121 offset0:64 offset1:96
	s_waitcnt lgkmcnt(0)
	ds_read_b128 v[0:3], v66
	ds_read_b128 v[4:7], v68
	ds_read_b128 v[8:11], v70
	ds_read_b128 v[12:15], v72
	ds_read_b128 v[16:19], v74
	ds_read_b128 v[20:23], v76
	ds_read_b128 v[24:27], v78
	ds_read_b128 v[28:31], v80
	s_waitcnt lgkmcnt(7)
	global_store_dwordx4 v[48:49], v[0:3], off
	s_waitcnt lgkmcnt(6)
	global_store_dwordx4 v[50:51], v[4:7], off
	s_waitcnt lgkmcnt(5)
	global_store_dwordx4 v[52:53], v[8:11], off
	s_waitcnt lgkmcnt(4)
	global_store_dwordx4 v[54:55], v[12:15], off
	s_waitcnt lgkmcnt(3)
	global_store_dwordx4 v[56:57], v[16:19], off
	s_waitcnt lgkmcnt(2)
	global_store_dwordx4 v[58:59], v[20:23], off
	s_waitcnt lgkmcnt(1)
	global_store_dwordx4 v[60:61], v[24:27], off
	s_waitcnt lgkmcnt(0)
	global_store_dwordx4 v[62:63], v[28:31], off
	s_waitcnt lgkmcnt(0)
	s_add_i32 s2, s2, s3
	s_add_i32 s6, s6, s7
	s_add_i32 s8, s8, s9
	s_cmpk_lt_i32 s2, 0x1580
	s_cbranch_scc1 .LBB0_1575
